# m3 + attention T5-bias add on near-diagonal tiles: 16 serial LDS round trips -> 5-deep rolling window of the same reads (strategy 2 applied to the attention loop)
# speedup vs baseline: 1.0057x; 1.0032x over previous
.LBB0_2974:
	v_add_u32_e32 v183, s36, v234
	ds_read_b64_tr_b16 v[178:179], v183 offset:24576
	ds_read_b64_tr_b16 v[180:181], v183 offset:25088
	s_waitcnt lgkmcnt(9)
	v_mfma_f32_32x32x16_bf16 v[98:113], v[82:85], v[130:133], v[2:17]
	v_add_f32_e32 v86, v66, v67
	v_add_f32_e32 v86, v68, v86
	v_add_f32_e32 v86, v69, v86
	v_add_f32_e32 v86, v70, v86
	v_add_f32_e32 v86, v71, v86
	v_cvt_pk_bf16_f32 v142, v66, v67
	v_cvt_pk_bf16_f32 v143, v68, v69
	ds_read_b64_tr_b16 v[174:175], v183 offset:28672
	ds_read_b64_tr_b16 v[176:177], v183 offset:29184
	v_add_f32_e32 v66, v72, v86
	s_waitcnt lgkmcnt(10)
	v_mfma_f32_32x32x16_bf16 v[82:97], v[166:169], v[130:133], v[2:17]
	v_add_f32_e32 v66, v73, v66
	v_add_f32_e32 v66, v74, v66
	v_add_f32_e32 v66, v75, v66
	v_cvt_pk_bf16_f32 v144, v70, v71
	v_cvt_pk_bf16_f32 v145, v72, v73
	ds_read_b64_tr_b16 v[166:167], v183 offset:25600
	ds_read_b64_tr_b16 v[168:169], v183 offset:26112
	s_waitcnt lgkmcnt(11)
	v_mfma_f32_32x32x16_bf16 v[98:113], v[170:173], v[126:129], v[98:113]
	v_add_f32_e32 v66, v76, v66
	v_add_f32_e32 v66, v77, v66
	v_add_f32_e32 v66, v78, v66
	v_add_f32_e32 v66, v79, v66
	v_cvt_pk_bf16_f32 v138, v74, v75
	v_cvt_pk_bf16_f32 v139, v76, v77
	ds_read_b64_tr_b16 v[74:75], v183 offset:29696
	ds_read_b64_tr_b16 v[76:77], v183 offset:30208
	s_waitcnt lgkmcnt(12)
	v_mfma_f32_32x32x16_bf16 v[82:97], v[158:161], v[126:129], v[82:97]
	v_add_f32_e32 v66, v80, v66
	v_add_f32_e32 v66, v81, v66
	v_add_f32_e32 v66, v50, v66
	v_add_f32_e32 v66, v51, v66
	v_cvt_pk_bf16_f32 v140, v78, v79
	v_cvt_pk_bf16_f32 v141, v80, v81
	ds_read_b64_tr_b16 v[70:71], v183 offset:26624
	ds_read_b64_tr_b16 v[72:73], v183 offset:27136
	s_waitcnt lgkmcnt(13)
	v_mfma_f32_32x32x16_bf16 v[98:113], v[162:165], v[118:121], v[98:113]
	v_add_f32_e32 v66, v52, v66
	v_add_f32_e32 v66, v53, v66
	v_add_f32_e32 v66, v54, v66
	v_add_f32_e32 v78, v55, v66
	v_cvt_pk_bf16_f32 v134, v50, v51
	v_cvt_pk_bf16_f32 v135, v52, v53
	ds_read_b64_tr_b16 v[66:67], v183 offset:30720
	ds_read_b64_tr_b16 v[68:69], v183 offset:31232
	s_waitcnt lgkmcnt(14)
	v_mfma_f32_32x32x16_bf16 v[82:97], v[150:153], v[118:121], v[82:97]
	v_add_f32_e32 v50, v56, v78
	v_add_f32_e32 v50, v57, v50
	v_add_f32_e32 v50, v58, v50
	v_add_f32_e32 v50, v59, v50
	v_cvt_pk_bf16_f32 v136, v54, v55
	v_cvt_pk_bf16_f32 v137, v56, v57
	ds_read_b64_tr_b16 v[54:55], v183 offset:27648
	ds_read_b64_tr_b16 v[56:57], v183 offset:28160
	s_waitcnt lgkmcnt(14)
	v_mfma_f32_32x32x16_bf16 v[98:113], v[154:157], v[114:117], v[98:113]
	v_add_f32_e32 v50, v60, v50
	v_add_f32_e32 v50, v61, v50
	v_add_f32_e32 v50, v62, v50
	v_add_f32_e32 v78, v63, v50
	v_cvt_pk_bf16_f32 v122, v58, v59
	v_cvt_pk_bf16_f32 v123, v60, v61
	ds_read_b64_tr_b16 v[50:51], v183 offset:31744
	ds_read_b64_tr_b16 v[52:53], v183 offset:32256
	v_mfma_f32_32x32x16_bf16 v[82:97], v[146:149], v[114:117], v[82:97]
	v_add_f32_e32 v58, v64, v78
	v_add_f32_e32 v58, v65, v58
	v_add_f32_e32 v58, 0, v58
	v_cvt_pk_bf16_f32 v124, v62, v63
	v_cvt_pk_bf16_f32 v125, v64, v65
	v_lshl_add_u64 v[216:217], v[210:211], 0, s[82:83]
	s_mov_b64 s[0:1], 0x7440000
	v_lshl_add_u64 v[60:61], v[216:217], 0, s[0:1]
	s_add_i32 s0, s35, s21
	s_mov_b32 s1, m0
	s_mov_b32 m0, s0
	s_nop 0
	global_load_lds_dwordx4 v[60:61], off
	s_mov_b32 m0, s1
	v_lshl_add_u64 v[218:219], v[214:215], 0, s[82:83]
	s_mov_b64 s[0:1], 0x8420000
	v_lshl_add_u64 v[60:61], v[218:219], 0, s[0:1]
	s_add_i32 s0, s24, s18
	s_mov_b32 s1, m0
	s_mov_b32 m0, s0
	s_nop 0
	global_load_lds_dwordx4 v[60:61], off
	s_mov_b32 m0, s1
	s_cmp_le_i32 s29, s17
	s_cbranch_scc1 .LBB0_2976
	ds_read2_b32 v[60:61], v188 offset0:122 offset1:123
	ds_read2_b32 v[240:241], v188 offset0:90 offset1:91
	ds_read2_b32 v[242:243], v188 offset0:120 offset1:121
	ds_read2_b32 v[244:245], v188 offset0:88 offset1:89
	ds_read2_b32 v[248:249], v188 offset0:114 offset1:115
	s_waitcnt lgkmcnt(4)
	v_pk_add_f32 v[98:99], v[98:99], v[60:61] op_sel:[0,1] op_sel_hi:[1,0]
	ds_read2_b32 v[60:61], v188 offset0:82 offset1:83
	s_waitcnt lgkmcnt(4)
	v_pk_add_f32 v[82:83], v[82:83], v[240:241] op_sel:[0,1] op_sel_hi:[1,0]
	ds_read2_b32 v[240:241], v188 offset0:112 offset1:113
	s_waitcnt lgkmcnt(4)
	v_pk_add_f32 v[100:101], v[100:101], v[242:243] op_sel:[0,1] op_sel_hi:[1,0]
	ds_read2_b32 v[242:243], v188 offset0:80 offset1:81
	s_waitcnt lgkmcnt(4)
	v_pk_add_f32 v[84:85], v[84:85], v[244:245] op_sel:[0,1] op_sel_hi:[1,0]
	ds_read2_b32 v[244:245], v188 offset0:106 offset1:107
	s_waitcnt lgkmcnt(4)
	v_pk_add_f32 v[102:103], v[102:103], v[248:249] op_sel:[0,1] op_sel_hi:[1,0]
	ds_read2_b32 v[248:249], v188 offset0:74 offset1:75
	s_waitcnt lgkmcnt(4)
	v_pk_add_f32 v[86:87], v[86:87], v[60:61] op_sel:[0,1] op_sel_hi:[1,0]
	ds_read2_b32 v[60:61], v188 offset0:104 offset1:105
	s_waitcnt lgkmcnt(4)
	v_pk_add_f32 v[104:105], v[104:105], v[240:241] op_sel:[0,1] op_sel_hi:[1,0]
	ds_read2_b32 v[240:241], v188 offset0:72 offset1:73
	s_waitcnt lgkmcnt(4)
	v_pk_add_f32 v[88:89], v[88:89], v[242:243] op_sel:[0,1] op_sel_hi:[1,0]
	ds_read2_b32 v[242:243], v188 offset0:98 offset1:99
	s_waitcnt lgkmcnt(4)
	v_pk_add_f32 v[106:107], v[106:107], v[244:245] op_sel:[0,1] op_sel_hi:[1,0]
	ds_read2_b32 v[244:245], v188 offset0:66 offset1:67
	s_waitcnt lgkmcnt(4)
	v_pk_add_f32 v[90:91], v[90:91], v[248:249] op_sel:[0,1] op_sel_hi:[1,0]
	ds_read2_b32 v[248:249], v188 offset0:96 offset1:97
	s_waitcnt lgkmcnt(4)
	v_pk_add_f32 v[108:109], v[108:109], v[60:61] op_sel:[0,1] op_sel_hi:[1,0]
	ds_read2_b32 v[60:61], v188 offset0:64 offset1:65
	s_waitcnt lgkmcnt(4)
	v_pk_add_f32 v[92:93], v[92:93], v[240:241] op_sel:[0,1] op_sel_hi:[1,0]
	s_waitcnt lgkmcnt(3)
	v_pk_add_f32 v[110:111], v[110:111], v[242:243] op_sel:[0,1] op_sel_hi:[1,0]
	s_waitcnt lgkmcnt(2)
	v_pk_add_f32 v[94:95], v[94:95], v[244:245] op_sel:[0,1] op_sel_hi:[1,0]
	s_waitcnt lgkmcnt(1)
	v_pk_add_f32 v[112:113], v[112:113], v[248:249] op_sel:[0,1] op_sel_hi:[1,0]
	s_waitcnt lgkmcnt(0)
	v_pk_add_f32 v[96:97], v[96:97], v[60:61] op_sel:[0,1] op_sel_hi:[1,0]

.LBB0_2979:
	s_add_i32 s0, s24, 0x2000
	s_cmpk_lg_i32 s24, 0x4000
	s_cselect_b32 s25, s0, 0
	v_add_u32_e32 v238, s35, v234
	ds_read_b64_tr_b16 v[158:159], v238 offset:24576
	ds_read_b64_tr_b16 v[160:161], v238 offset:25088
	s_waitcnt lgkmcnt(9)
	v_mfma_f32_32x32x16_bf16 v[66:81], v[58:61], v[130:133], v[2:17]
	v_add_f32_e32 v50, v98, v99
	v_add_f32_e32 v50, v100, v50
	v_add_f32_e32 v50, v101, v50
	v_add_f32_e32 v50, v102, v50
	v_add_f32_e32 v50, v103, v50
	v_cvt_pk_bf16_f32 v142, v98, v99
	v_cvt_pk_bf16_f32 v143, v100, v101
	ds_read_b64_tr_b16 v[154:155], v238 offset:28672
	ds_read_b64_tr_b16 v[156:157], v238 offset:29184
	v_add_f32_e32 v50, v104, v50
	v_add_f32_e32 v50, v105, v50
	v_add_f32_e32 v50, v106, v50
	v_add_f32_e32 v98, v107, v50
	s_waitcnt lgkmcnt(10)
	v_mfma_f32_32x32x16_bf16 v[50:65], v[146:149], v[130:133], v[2:17]
	v_cvt_pk_bf16_f32 v144, v102, v103
	v_cvt_pk_bf16_f32 v145, v104, v105
	ds_read_b64_tr_b16 v[150:151], v238 offset:25600
	ds_read_b64_tr_b16 v[152:153], v238 offset:26112
	s_waitcnt lgkmcnt(11)
	v_mfma_f32_32x32x16_bf16 v[66:81], v[174:177], v[126:129], v[66:81]
	v_add_f32_e32 v98, v108, v98
	v_add_f32_e32 v98, v109, v98
	v_add_f32_e32 v98, v110, v98
	v_add_f32_e32 v98, v111, v98
	v_cvt_pk_bf16_f32 v138, v106, v107
	v_cvt_pk_bf16_f32 v139, v108, v109
	ds_read_b64_tr_b16 v[146:147], v238 offset:29696
	ds_read_b64_tr_b16 v[148:149], v238 offset:30208
	s_waitcnt lgkmcnt(12)
	v_mfma_f32_32x32x16_bf16 v[50:65], v[162:165], v[126:129], v[50:65]
	v_add_f32_e32 v98, v112, v98
	v_add_f32_e32 v98, v113, v98
	v_add_f32_e32 v98, v82, v98
	v_add_f32_e32 v98, v83, v98
	v_cvt_pk_bf16_f32 v140, v110, v111
	v_cvt_pk_bf16_f32 v141, v112, v113
	ds_read_b64_tr_b16 v[106:107], v238 offset:26624
	ds_read_b64_tr_b16 v[108:109], v238 offset:27136
	s_waitcnt lgkmcnt(13)
	v_mfma_f32_32x32x16_bf16 v[66:81], v[178:181], v[118:121], v[66:81]
	v_add_f32_e32 v98, v84, v98
	v_add_f32_e32 v98, v85, v98
	v_add_f32_e32 v98, v86, v98
	v_add_f32_e32 v98, v87, v98
	v_cvt_pk_bf16_f32 v134, v82, v83
	v_cvt_pk_bf16_f32 v135, v84, v85
	ds_read_b64_tr_b16 v[102:103], v238 offset:30720
	ds_read_b64_tr_b16 v[104:105], v238 offset:31232
	s_waitcnt lgkmcnt(14)
	v_mfma_f32_32x32x16_bf16 v[50:65], v[166:169], v[118:121], v[50:65]
	v_add_f32_e32 v82, v88, v98
	v_add_f32_e32 v82, v89, v82
	v_add_f32_e32 v82, v90, v82
	v_add_f32_e32 v82, v91, v82
	v_cvt_pk_bf16_f32 v136, v86, v87
	v_cvt_pk_bf16_f32 v137, v88, v89
	ds_read_b64_tr_b16 v[98:99], v238 offset:27648
	ds_read_b64_tr_b16 v[100:101], v238 offset:28160
	s_waitcnt lgkmcnt(14)
	v_mfma_f32_32x32x16_bf16 v[66:81], v[182:185], v[114:117], v[66:81]
	v_add_f32_e32 v82, v92, v82
	v_add_f32_e32 v82, v93, v82
	v_add_f32_e32 v82, v94, v82
	v_add_f32_e32 v82, v95, v82
	v_cvt_pk_bf16_f32 v122, v90, v91
	v_cvt_pk_bf16_f32 v123, v92, v93
	ds_read_b64_tr_b16 v[86:87], v238 offset:31744
	ds_read_b64_tr_b16 v[88:89], v238 offset:32256
	v_mfma_f32_32x32x16_bf16 v[50:65], v[170:173], v[114:117], v[50:65]
	v_add_f32_e32 v82, v96, v82
	v_add_f32_e32 v82, v97, v82
	v_add_f32_e32 v82, 0, v82
	v_cvt_pk_bf16_f32 v124, v94, v95
	v_cvt_pk_bf16_f32 v125, v96, v97
	s_mov_b64 s[0:1], 0x7450000
	v_lshl_add_u64 v[84:85], v[216:217], 0, s[0:1]
	s_add_i32 s0, s24, s21
	s_mov_b32 s1, m0
	s_mov_b32 m0, s0
	s_nop 0
	global_load_lds_dwordx4 v[84:85], off
	s_mov_b32 m0, s1
	s_mov_b64 s[0:1], 0x8430000
	v_lshl_add_u64 v[84:85], v[218:219], 0, s[0:1]
	s_add_i32 s0, s25, s18
	s_add_i32 s1, s29, 64
	s_cmp_le_i32 s1, s17
	s_mov_b32 s1, m0
	s_mov_b32 m0, s0
	s_nop 0
	global_load_lds_dwordx4 v[84:85], off
	s_mov_b32 m0, s1
	s_cbranch_scc1 .LBB0_2981
	ds_read2_b32 v[84:85], v188 offset0:58 offset1:59
	ds_read2_b32 v[240:241], v188 offset0:26 offset1:27
	ds_read2_b32 v[242:243], v188 offset0:56 offset1:57
	ds_read2_b32 v[244:245], v188 offset0:24 offset1:25
	ds_read2_b32 v[248:249], v188 offset0:50 offset1:51
	s_waitcnt lgkmcnt(4)
	v_pk_add_f32 v[66:67], v[66:67], v[84:85] op_sel:[0,1] op_sel_hi:[1,0]
	ds_read2_b32 v[84:85], v188 offset0:18 offset1:19
	s_waitcnt lgkmcnt(4)
	v_pk_add_f32 v[50:51], v[50:51], v[240:241] op_sel:[0,1] op_sel_hi:[1,0]
	ds_read2_b32 v[240:241], v188 offset0:48 offset1:49
	s_waitcnt lgkmcnt(4)
	v_pk_add_f32 v[68:69], v[68:69], v[242:243] op_sel:[0,1] op_sel_hi:[1,0]
	ds_read2_b32 v[242:243], v188 offset0:16 offset1:17
	s_waitcnt lgkmcnt(4)
	v_pk_add_f32 v[52:53], v[52:53], v[244:245] op_sel:[0,1] op_sel_hi:[1,0]
	ds_read2_b32 v[244:245], v188 offset0:42 offset1:43
	s_waitcnt lgkmcnt(4)
	v_pk_add_f32 v[70:71], v[70:71], v[248:249] op_sel:[0,1] op_sel_hi:[1,0]
	ds_read2_b32 v[248:249], v188 offset0:10 offset1:11
	s_waitcnt lgkmcnt(4)
	v_pk_add_f32 v[54:55], v[54:55], v[84:85] op_sel:[0,1] op_sel_hi:[1,0]
	ds_read2_b32 v[84:85], v188 offset0:40 offset1:41
	s_waitcnt lgkmcnt(4)
	v_pk_add_f32 v[72:73], v[72:73], v[240:241] op_sel:[0,1] op_sel_hi:[1,0]
	ds_read2_b32 v[240:241], v188 offset0:8 offset1:9
	s_waitcnt lgkmcnt(4)
	v_pk_add_f32 v[56:57], v[56:57], v[242:243] op_sel:[0,1] op_sel_hi:[1,0]
	ds_read2_b32 v[242:243], v188 offset0:34 offset1:35
	s_waitcnt lgkmcnt(4)
	v_pk_add_f32 v[74:75], v[74:75], v[244:245] op_sel:[0,1] op_sel_hi:[1,0]
	ds_read2_b32 v[244:245], v188 offset0:2 offset1:3
	s_waitcnt lgkmcnt(4)
	v_pk_add_f32 v[58:59], v[58:59], v[248:249] op_sel:[0,1] op_sel_hi:[1,0]
	ds_read2_b32 v[248:249], v188 offset0:32 offset1:33
	s_waitcnt lgkmcnt(4)
	v_pk_add_f32 v[76:77], v[76:77], v[84:85] op_sel:[0,1] op_sel_hi:[1,0]
	ds_read2_b32 v[84:85], v188 offset1:1
	s_waitcnt lgkmcnt(4)
	v_pk_add_f32 v[60:61], v[60:61], v[240:241] op_sel:[0,1] op_sel_hi:[1,0]
	s_waitcnt lgkmcnt(3)
	v_pk_add_f32 v[78:79], v[78:79], v[242:243] op_sel:[0,1] op_sel_hi:[1,0]
	s_waitcnt lgkmcnt(2)
	v_pk_add_f32 v[62:63], v[62:63], v[244:245] op_sel:[0,1] op_sel_hi:[1,0]
	s_waitcnt lgkmcnt(1)
	v_pk_add_f32 v[80:81], v[80:81], v[248:249] op_sel:[0,1] op_sel_hi:[1,0]
	s_waitcnt lgkmcnt(0)
	v_pk_add_f32 v[64:65], v[64:65], v[84:85] op_sel:[0,1] op_sel_hi:[1,0]
